# R7_FIN rows: layer-norm gain/bias vectors loaded once per phase; v / z row pieces requested together with the y rows
# baseline (speedup 1.0000x reference)
; __device__ __forceinline__ int ltid() { int t = threadIdx.x; asm volatile("" : "+v"(t)); return t; }
; __device__ __forceinline__ float blo(unsigned u) { return __uint_as_float(u << 16); }
; __device__ __forceinline__ float bhi(unsigned u) { return __uint_as_float(u & 0xffff0000u); }
; __device__ __forceinline__ void ph_r7_fin(const P& p, int j) {
;   bfr* Y = (bfr*)(p.ACT + A_Y); const bfr* RK = (const bfr*)(p.ACT + A_RKVZ); const float* BON = (const float*)(p.ACT + A_BON);
;   const float* lg = p.r7_ln_g + (size_t)j * 1024; const float* lb = p.r7_ln_b + (size_t)j * 1024;
;   const int lane = ltid() & 63, wid = ltid() >> 6;
;   for (int it = blockIdx.x; it < 4160; it += gridDim.x) {
;     int row = it * 8 + wid, ch = lane * 16, hd = lane >> 2;
;     float y[16], v[16], z[16];
; #pragma unroll
;     for (int i = 0; i < 2; i++) {
;       uint4 u = *(const uint4*)(Y + (size_t)row * 1024 + ch + i * 8); const uint4 u2 = *(const uint4*)(R7_Y2 + (size_t)row * 1024 + ch + i * 8);
;       y[i * 8 + 0] = blo(u.x) + blo(u2.x); y[i * 8 + 1] = bhi(u.x) + bhi(u2.x); y[i * 8 + 2] = blo(u.y) + blo(u2.y); y[i * 8 + 3] = bhi(u.y) + bhi(u2.y); y[i * 8 + 4] = blo(u.z) + blo(u2.z); y[i * 8 + 5] = bhi(u.z) + bhi(u2.z); y[i * 8 + 6] = blo(u.w) + blo(u2.w); y[i * 8 + 7] = bhi(u.w) + bhi(u2.w);
;       u = *(const uint4*)(RK + (size_t)row * 4096 + 2048 + ch + i * 8);
;       v[i * 8 + 0] = blo(u.x); v[i * 8 + 1] = bhi(u.x); v[i * 8 + 2] = blo(u.y); v[i * 8 + 3] = bhi(u.y); v[i * 8 + 4] = blo(u.z); v[i * 8 + 5] = bhi(u.z); v[i * 8 + 6] = blo(u.w); v[i * 8 + 7] = bhi(u.w);
;       u = *(const uint4*)(RK + (size_t)row * 4096 + 3072 + ch + i * 8);
;       z[i * 8 + 0] = blo(u.x); z[i * 8 + 1] = bhi(u.x); z[i * 8 + 2] = blo(u.y); z[i * 8 + 3] = bhi(u.y); z[i * 8 + 4] = blo(u.z); z[i * 8 + 5] = bhi(u.z); z[i * 8 + 6] = blo(u.w); z[i * 8 + 7] = bhi(u.w);
;     }
.LBB0_130:
	s_andn2_b64 vcc, exec, s[6:7]
	s_cbranch_vccnz .LBB0_275
	v_readlane_b32 s6, v254, 59
	v_readlane_b32 s7, v254, 60
	s_cmp_lt_i32 s6, 16
	s_mov_b64 s[6:7], -1
	s_cbranch_scc1 .LBB0_183
	v_readlane_b32 s6, v254, 59
	v_readlane_b32 s7, v254, 60
	s_cmp_gt_i32 s6, 16
	s_mov_b64 s[6:7], -1
	s_cbranch_scc0 .LBB0_137
	v_readlane_b32 s6, v251, 13
	v_readlane_b32 s7, v251, 14
	v_mov_b32_e32 v2, v168
	v_mov_b32_e32 v0, v168
	s_andn2_b64 vcc, exec, s[6:7]
	s_mov_b32 s19, 0x800000
	s_mov_b64 s[30:31], 0x1000
	s_cbranch_vccnz .LBB0_136
	v_readlane_b32 s6, v254, 57
	v_and_b32_e32 v7, 64, v175
	v_readlane_b32 s7, v254, 58
	v_xor_b32_e32 v3, 1, v175
	v_add_u32_e32 v7, 64, v7
	s_mov_b32 s8, s6
	s_ashr_i32 s9, s6, 31
	v_writelane_b32 v254, s6, 57
	v_cmp_lt_i32_e32 vcc, v3, v7
	v_readlane_b32 s40, v253, 57
	v_writelane_b32 v254, s7, 58
	v_cndmask_b32_e32 v3, v175, v3, vcc
	s_lshl_b64 s[6:7], s[8:9], 12
	v_readlane_b32 s48, v254, 1
	v_lshlrev_b32_e32 v71, 2, v3
	v_xor_b32_e32 v3, 2, v175
	v_readlane_b32 s49, v254, 2
	s_add_u32 s8, s48, s6
	v_cmp_lt_i32_e32 vcc, v3, v7
	v_readlane_b32 s46, v253, 63
	s_addc_u32 s9, s49, s7
	v_cndmask_b32_e32 v3, v175, v3, vcc
	v_readlane_b32 s10, v251, 15
	v_readlane_b32 s47, v254, 0
	s_add_u32 s6, s46, s6
	v_and_b32_e32 v6, 63, v2
	v_lshlrev_b32_e32 v104, 2, v3
	v_and_b32_e32 v2, 60, v2
	v_mov_b32_e32 v3, v1
	v_readlane_b32 s11, v251, 16
	s_addc_u32 s7, s47, s7
	v_ashrrev_i32_e32 v5, 6, v0
	s_waitcnt vmcnt(0)
	v_lshl_add_u64 v[36:37], s[10:11], 0, v[2:3]
	v_lshlrev_b32_e32 v2, 6, v6
	v_lshl_add_u64 v[38:39], s[6:7], 0, v[2:3]
	v_readlane_b32 s6, v251, 17
	v_lshlrev_b32_e32 v0, 5, v6
	v_readlane_b32 s7, v251, 18
	v_lshlrev_b32_e32 v4, 4, v6
	v_lshl_add_u64 v[34:35], s[88:89], 0, v[0:1]
	v_lshl_add_u64 v[42:43], s[6:7], 0, v[0:1]
	v_readlane_b32 s6, v253, 12
	v_lshl_add_u64 v[40:41], s[8:9], 0, v[2:3]
	v_lshlrev_b32_e32 v0, 1, v4
	v_add_u32_e32 v44, s6, v5
	s_mov_b32 s6, s84
	v_readlane_b32 s41, v253, 58
	v_readlane_b32 s42, v253, 59
	v_readlane_b32 s43, v253, 60
	v_readlane_b32 s44, v253, 61
	v_readlane_b32 s45, v253, 62
	v_readlane_b32 s50, v254, 3
	v_readlane_b32 s51, v254, 4
	v_readlane_b32 s52, v254, 5
	v_readlane_b32 s53, v254, 6
	v_readlane_b32 s54, v254, 7
	v_readlane_b32 s55, v254, 8
	global_load_dwordx4 v[188:191], v[38:39], off
	global_load_dwordx4 v[192:195], v[38:39], off offset:16
	global_load_dwordx4 v[196:199], v[38:39], off offset:32
	global_load_dwordx4 v[200:203], v[38:39], off offset:48
	global_load_dwordx4 v[204:207], v[40:41], off
	global_load_dwordx4 v[208:211], v[40:41], off offset:16
	global_load_dwordx4 v[212:215], v[40:41], off offset:32
	global_load_dwordx4 v[216:219], v[40:41], off offset:48
.LBB0_135:
	v_ashrrev_i32_e32 v45, 31, v44
	v_lshlrev_b64 v[2:3], 11, v[44:45]
	v_lshlrev_b64 v[4:5], 13, v[44:45]
	v_lshl_add_u64 v[46:47], v[34:35], 0, v[2:3]
	v_lshl_add_u64 v[4:5], s[38:39], 0, v[4:5]
	v_lshl_add_u64 v[2:3], v[42:43], 0, v[2:3]
	v_lshl_add_u64 v[22:23], v[4:5], 0, v[0:1]
	global_load_dwordx4 v[10:13], v[46:47], off offset:16
	global_load_dwordx4 v[4:7], v[46:47], off
	global_load_dwordx4 v[14:17], v[2:3], off offset:16
	global_load_dwordx4 v[18:21], v[2:3], off
	v_add_co_u32_e32 v28, vcc, s33, v22
	v_lshl_add_u64 v[24:25], v[22:23], 0, s[30:31]
	s_mov_b64 s[8:9], 0x1800
	v_addc_co_u32_e32 v29, vcc, 0, v23, vcc
	v_lshl_add_u64 v[26:27], v[22:23], 0, s[8:9]
	global_load_dwordx4 v[118:121], v[28:29], off
	s_nop 0
	global_load_dwordx4 v[22:25], v[24:25], off offset:16
	s_nop 0
	global_load_dwordx4 v[122:125], v[28:29], off offset:2048
	s_nop 0
	global_load_dwordx4 v[26:29], v[26:27], off offset:16
	s_add_i32 s6, s6, s96
	s_cmpk_gt_i32 s6, 0x103f
	s_waitcnt vmcnt(4)
	v_lshlrev_b32_e32 v91, 16, v12
	v_lshlrev_b32_e32 v72, 16, v4
	v_and_b32_e32 v73, 0xffff0000, v4
	v_lshlrev_b32_e32 v74, 16, v18
	v_and_b32_e32 v75, 0xffff0000, v18
	v_lshlrev_b32_e32 v86, 16, v5
	v_lshlrev_b32_e32 v88, 16, v19
	v_and_b32_e32 v87, 0xffff0000, v5
	v_and_b32_e32 v89, 0xffff0000, v19
	v_lshlrev_b32_e32 v4, 16, v20
	v_and_b32_e32 v5, 0xffff0000, v20
	v_lshlrev_b32_e32 v8, 16, v21
	v_and_b32_e32 v9, 0xffff0000, v21
	v_and_b32_e32 v90, 0xffff0000, v12
	v_pk_add_f32 v[88:89], v[86:87], v[88:89]
	v_pk_add_f32 v[72:73], v[72:73], v[74:75]
	v_lshlrev_b32_e32 v2, 16, v6
	v_and_b32_e32 v3, 0xffff0000, v6
	v_pk_add_f32 v[102:103], v[2:3], v[4:5]
	v_lshlrev_b32_e32 v6, 16, v7
	v_and_b32_e32 v7, 0xffff0000, v7
	v_pk_add_f32 v[100:101], v[6:7], v[8:9]
	v_lshlrev_b32_e32 v93, 16, v16
	v_and_b32_e32 v92, 0xffff0000, v16
	v_pk_add_f32 v[90:91], v[90:91], v[92:93]
	s_waitcnt vmcnt(2)
	v_lshlrev_b32_e32 v60, 16, v118
	v_and_b32_e32 v61, 0xffff0000, v118
	v_lshlrev_b32_e32 v56, 16, v119
	v_and_b32_e32 v57, 0xffff0000, v119
	v_lshlrev_b32_e32 v54, 16, v120
	v_and_b32_e32 v55, 0xffff0000, v120
	v_lshlrev_b32_e32 v52, 16, v121
	v_and_b32_e32 v53, 0xffff0000, v121
	v_lshlrev_b32_e32 v68, 16, v22
	v_and_b32_e32 v69, 0xffff0000, v22
	v_lshlrev_b32_e32 v66, 16, v23
	v_and_b32_e32 v67, 0xffff0000, v23
	v_lshlrev_b32_e32 v62, 16, v24
	v_and_b32_e32 v63, 0xffff0000, v24
	v_lshlrev_b32_e32 v50, 16, v25
	v_and_b32_e32 v51, 0xffff0000, v25
	s_waitcnt vmcnt(0)
; __device__ __forceinline__ float blo(unsigned u) { return __uint_as_float(u << 16); }
; __device__ __forceinline__ float bhi(unsigned u) { return __uint_as_float(u & 0xffff0000u); }
; __device__ __forceinline__ void ph_r7_fin(const P& p, int j) {
;     ...
;       uint4 u = *(const uint4*)(Y + (size_t)row * 1024 + ch + i * 8); const uint4 u2 = *(const uint4*)(R7_Y2 + (size_t)row * 1024 + ch + i * 8);
;       y[i * 8 + 0] = blo(u.x) + blo(u2.x); y[i * 8 + 1] = bhi(u.x) + bhi(u2.x); y[i * 8 + 2] = blo(u.y) + blo(u2.y); y[i * 8 + 3] = bhi(u.y) + bhi(u2.y); y[i * 8 + 4] = blo(u.z) + blo(u2.z); y[i * 8 + 5] = bhi(u.z) + bhi(u2.z); y[i * 8 + 6] = blo(u.w) + blo(u2.w); y[i * 8 + 7] = bhi(u.w) + bhi(u2.w);
;       u = *(const uint4*)(RK + (size_t)row * 4096 + 2048 + ch + i * 8);
;       v[i * 8 + 0] = blo(u.x); v[i * 8 + 1] = bhi(u.x); v[i * 8 + 2] = blo(u.y); v[i * 8 + 3] = bhi(u.y); v[i * 8 + 4] = blo(u.z); v[i * 8 + 5] = bhi(u.z); v[i * 8 + 6] = blo(u.w); v[i * 8 + 7] = bhi(u.w);
;       u = *(const uint4*)(RK + (size_t)row * 4096 + 3072 + ch + i * 8);
;       z[i * 8 + 0] = blo(u.x); z[i * 8 + 1] = bhi(u.x); z[i * 8 + 2] = blo(u.y); z[i * 8 + 3] = bhi(u.y); z[i * 8 + 4] = blo(u.z); z[i * 8 + 5] = bhi(u.z); z[i * 8 + 6] = blo(u.w); z[i * 8 + 7] = bhi(u.w);
;     }
;     float s = 0.f;
; #pragma unroll
;     for (int e = 0; e < 16; e++) s += y[e];
;     s += __shfl_xor(s, 1); s += __shfl_xor(s, 2); float mean = s * (1.f / 64.f);
;     float q = 0.f;
; #pragma unroll
;     for (int e = 0; e < 16; e++) { float dlt = y[e] - mean; q += dlt * dlt; }
;     q += __shfl_xor(q, 1); q += __shfl_xor(q, 2); float rs = rsqrtf(q * (1.f / 64.f) + 64e-5f);
;     float bon = BON[(size_t)row * 16 + hd] + BON[(size_t)(R_ + row) * 16 + hd];
	v_lshlrev_b32_e32 v94, 16, v122
	v_and_b32_e32 v95, 0xffff0000, v122
	v_lshlrev_b32_e32 v96, 16, v123
	v_and_b32_e32 v97, 0xffff0000, v123
	v_lshlrev_b32_e32 v98, 16, v124
	v_and_b32_e32 v99, 0xffff0000, v124
	v_lshlrev_b32_e32 v80, 16, v125
	v_and_b32_e32 v81, 0xffff0000, v125
	v_lshlrev_b32_e32 v19, 16, v10
	v_lshlrev_b32_e32 v21, 16, v14
	v_and_b32_e32 v18, 0xffff0000, v10
	v_and_b32_e32 v20, 0xffff0000, v14
	v_pk_add_f32 v[76:77], v[18:19], v[20:21]
	v_lshlrev_b32_e32 v19, 16, v11
	v_lshlrev_b32_e32 v21, 16, v15
	v_and_b32_e32 v18, 0xffff0000, v11
	v_and_b32_e32 v20, 0xffff0000, v15
	v_lshlrev_b32_e32 v11, 16, v13
	v_lshlrev_b32_e32 v15, 16, v17
	v_and_b32_e32 v10, 0xffff0000, v13
	v_and_b32_e32 v14, 0xffff0000, v17
	v_pk_add_f32 v[84:85], v[10:11], v[14:15]
	v_lshlrev_b64 v[10:11], 6, v[44:45]
	v_lshl_add_u64 v[10:11], v[36:37], 0, v[10:11]
	global_load_dword v12, v[10:11], off
	v_add_u32_e32 v10, 0x8200, v44
	v_ashrrev_i32_e32 v11, 31, v10
	v_lshlrev_b64 v[10:11], 6, v[10:11]
	v_lshl_add_u64 v[10:11], v[36:37], 0, v[10:11]
	global_load_dword v10, v[10:11], off
	v_mul_f32_e32 v45, 0xbfb8aa3b, v99
	v_exp_f32_e32 v45, v45
	v_mul_f32_e32 v2, 0xbfb8aa3b, v98
	v_exp_f32_e32 v2, v2
	v_pk_add_f32 v[78:79], v[18:19], v[20:21]
	v_add_f32_e32 v45, 1.0, v45
	v_rcp_f32_e32 v107, v45
	v_mul_f32_e32 v45, 0xbfb8aa3b, v96
	v_exp_f32_e32 v45, v45
	v_add_f32_e32 v2, 1.0, v2
	v_lshlrev_b32_e32 v82, 16, v26
	v_and_b32_e32 v83, 0xffff0000, v26
	v_add_f32_e32 v45, 1.0, v45
	v_rcp_f32_e32 v86, v45
	v_mul_f32_e32 v45, 0xbfb8aa3b, v97
	v_exp_f32_e32 v45, v45
	v_lshlrev_b32_e32 v64, 16, v27
	v_and_b32_e32 v65, 0xffff0000, v27
	v_lshlrev_b32_e32 v58, 16, v28
	v_add_f32_e32 v45, 1.0, v45
	v_rcp_f32_e32 v87, v45
	v_add_f32_e32 v45, 0, v72
	v_add_f32_e32 v45, v73, v45
	v_add_f32_e32 v45, v88, v45
	v_add_f32_e32 v45, v89, v45
	v_add_f32_e32 v45, v102, v45
	v_add_f32_e32 v45, v103, v45
	v_add_f32_e32 v45, v100, v45
	v_add_f32_e32 v45, v101, v45
	v_add_f32_e32 v45, v45, v77
	v_and_b32_e32 v59, 0xffff0000, v28
	v_lshlrev_b32_e32 v48, 16, v29
	v_and_b32_e32 v49, 0xffff0000, v29
	v_rcp_f32_e32 v106, v2
	v_add_f32_e32 v45, v76, v45
	v_add_f32_e32 v45, v79, v45
	v_add_f32_e32 v45, v78, v45
	v_add_f32_e32 v45, v91, v45
	v_add_f32_e32 v45, v90, v45
	v_add_f32_e32 v45, v85, v45
	v_add_f32_e32 v45, v84, v45
	ds_bpermute_b32 v92, v71, v45
	v_mul_f32_e32 v74, 0xbfb8aa3b, v94
	v_mul_f32_e32 v75, 0xbfb8aa3b, v95
	v_exp_f32_e32 v74, v74
	v_exp_f32_e32 v75, v75
	s_waitcnt lgkmcnt(0)
	v_add_f32_e32 v45, v45, v92
	ds_bpermute_b32 v92, v104, v45
	v_add_f32_e32 v74, 1.0, v74
	v_add_f32_e32 v75, 1.0, v75
	v_rcp_f32_e32 v74, v74
	v_rcp_f32_e32 v75, v75
	s_waitcnt lgkmcnt(0)
	v_add_f32_e32 v45, v45, v92
	v_mul_f32_e32 v92, 0x3c800000, v45
	v_mul_f32_e32 v45, 0xbfb8aa3b, v80
	v_exp_f32_e32 v45, v45
	v_pk_mul_f32 v[74:75], v[74:75], v[94:95]
	v_pk_add_f32 v[94:95], v[72:73], v[92:93] op_sel_hi:[1,0] neg_lo:[0,1] neg_hi:[0,1]
	v_pk_mul_f32 v[98:99], v[106:107], v[98:99]
	v_add_f32_e32 v45, 1.0, v45
	v_rcp_f32_e32 v114, v45
	v_mul_f32_e32 v45, 0xbfb8aa3b, v81
	v_exp_f32_e32 v45, v45
	v_pk_mul_f32 v[86:87], v[86:87], v[96:97]
	v_pk_mul_f32 v[96:97], v[94:95], v[94:95]
	v_pk_add_f32 v[106:107], v[88:89], v[92:93] op_sel_hi:[1,0] neg_lo:[0,1] neg_hi:[0,1]
	v_add_f32_e32 v45, 1.0, v45
	v_rcp_f32_e32 v115, v45
	v_mul_f32_e32 v45, 0xbfb8aa3b, v82
	v_exp_f32_e32 v45, v45
	v_pk_mul_f32 v[108:109], v[106:107], v[106:107]
	v_pk_add_f32 v[102:103], v[102:103], v[92:93] op_sel_hi:[1,0] neg_lo:[0,1] neg_hi:[0,1]
	v_pk_add_f32 v[100:101], v[100:101], v[92:93] op_sel_hi:[1,0] neg_lo:[0,1] neg_hi:[0,1]
	v_add_f32_e32 v45, 1.0, v45
	v_rcp_f32_e32 v116, v45
	v_mul_f32_e32 v45, 0xbfb8aa3b, v83
	v_exp_f32_e32 v45, v45
	v_pk_mul_f32 v[110:111], v[102:103], v[102:103]
	v_pk_mul_f32 v[112:113], v[100:101], v[100:101]
	s_waitcnt vmcnt(0)
; __device__ __forceinline__ unsigned pk2(float a, float b) { return cvtpk(a, b); }
; __device__ __forceinline__ float siluf(float x) { return x * sigm(x); }
; __device__ __forceinline__ void ph_r7_fin(const P& p, int j) {
;     ...
;     q += __shfl_xor(q, 1); q += __shfl_xor(q, 2); float rs = rsqrtf(q * (1.f / 64.f) + 64e-5f);
;     float bon = BON[(size_t)row * 16 + hd] + BON[(size_t)(R_ + row) * 16 + hd];
;     float o[16];
; #pragma unroll
;     for (int e = 0; e < 16; e++) { float yn = (y[e] - mean) * rs * lg[ch + e] + lb[ch + e]; o[e] = (yn + bon * v[e]) * siluf(z[e]); }
; #pragma unroll
;     for (int i = 0; i < 2; i++)
;       *(uint4*)(Y + (size_t)row * 1024 + ch + i * 8) = uint4{pk2(o[i * 8], o[i * 8 + 1]), pk2(o[i * 8 + 2], o[i * 8 + 3]), pk2(o[i * 8 + 4], o[i * 8 + 5]), pk2(o[i * 8 + 6], o[i * 8 + 7])};
	v_add_f32_e32 v70, v12, v10
	v_add_f32_e32 v45, 1.0, v45
	v_rcp_f32_e32 v117, v45
	v_add_f32_e32 v45, v96, v97
	v_add_f32_e32 v45, v108, v45
	v_add_f32_e32 v45, v109, v45
	v_add_f32_e32 v45, v110, v45
	v_add_f32_e32 v45, v111, v45
	v_pk_add_f32 v[76:77], v[76:77], v[92:93] op_sel_hi:[1,0] neg_lo:[0,1] neg_hi:[0,1]
	v_add_f32_e32 v45, v112, v45
	v_pk_add_f32 v[88:89], v[90:91], v[92:93] op_sel_hi:[1,0] neg_lo:[0,1] neg_hi:[0,1]
	v_pk_add_f32 v[72:73], v[84:85], v[92:93] op_sel_hi:[1,0] neg_lo:[0,1] neg_hi:[0,1]
	v_pk_add_f32 v[78:79], v[78:79], v[92:93] op_sel_hi:[1,0] neg_lo:[0,1] neg_hi:[0,1]
	v_pk_mul_f32 v[92:93], v[76:77], v[76:77]
	v_add_f32_e32 v45, v113, v45
	v_add_f32_e32 v45, v93, v45
	v_pk_mul_f32 v[80:81], v[114:115], v[80:81]
	v_pk_mul_f32 v[114:115], v[78:79], v[78:79]
	v_add_f32_e32 v45, v92, v45
	v_add_f32_e32 v45, v115, v45
	v_pk_mul_f32 v[90:91], v[88:89], v[88:89]
	v_add_f32_e32 v45, v114, v45
	v_add_f32_e32 v45, v91, v45
	v_pk_mul_f32 v[84:85], v[72:73], v[72:73]
	v_add_f32_e32 v45, v90, v45
	v_add_f32_e32 v45, v85, v45
	v_add_f32_e32 v45, v84, v45
	ds_bpermute_b32 v84, v71, v45
	v_pk_mul_f32 v[82:83], v[116:117], v[82:83]
	v_add_u32_e32 v44, s64, v44
	s_waitcnt lgkmcnt(0)
	v_add_f32_e32 v45, v45, v84
	ds_bpermute_b32 v84, v104, v45
	s_waitcnt lgkmcnt(0)
	v_add_f32_e32 v45, v45, v84
	v_mov_b32_e32 v84, 0x3a27c5ac
	v_fmamk_f32 v45, v45, 0x3c800000, v84
	v_cmp_gt_f32_e32 vcc, s19, v45
	v_mul_f32_e32 v84, 0x4b800000, v45
	s_nop 0
	v_cndmask_b32_e32 v45, v45, v84, vcc
	v_rsq_f32_e32 v45, v45
	s_nop 0
	v_mul_f32_e32 v84, 0x45800000, v45
	v_cndmask_b32_e32 v84, v45, v84, vcc
	v_pk_mul_f32 v[90:91], v[94:95], v[84:85] op_sel_hi:[1,0]
	s_waitcnt vmcnt(0)
	v_pk_fma_f32 v[26:27], v[188:189], v[90:91], v[204:205]
	v_pk_mul_f32 v[30:31], v[106:107], v[84:85] op_sel_hi:[1,0]
	v_pk_fma_f32 v[26:27], v[70:71], v[60:61], v[26:27] op_sel_hi:[0,1,1]
	v_pk_fma_f32 v[28:29], v[190:191], v[30:31], v[206:207]
	v_pk_mul_f32 v[30:31], v[102:103], v[84:85] op_sel_hi:[1,0]
	v_pk_fma_f32 v[28:29], v[70:71], v[56:57], v[28:29] op_sel_hi:[0,1,1]
	v_pk_fma_f32 v[18:19], v[192:193], v[30:31], v[208:209]
	v_pk_mul_f32 v[22:23], v[100:101], v[84:85] op_sel_hi:[1,0]
	v_pk_fma_f32 v[18:19], v[70:71], v[54:55], v[18:19] op_sel_hi:[0,1,1]
	v_pk_fma_f32 v[20:21], v[194:195], v[22:23], v[210:211]
	v_pk_mul_f32 v[22:23], v[76:77], v[84:85] op_sel_hi:[1,0]
	v_pk_fma_f32 v[20:21], v[70:71], v[52:53], v[20:21] op_sel_hi:[0,1,1]
	v_pk_fma_f32 v[10:11], v[196:197], v[22:23], v[212:213] op_sel:[0,1,0] op_sel_hi:[1,0,1]
	v_mul_f32_e32 v14, 0xbfb8aa3b, v64
	v_mul_f32_e32 v15, 0xbfb8aa3b, v65
	v_exp_f32_e32 v14, v14
	v_exp_f32_e32 v15, v15
	v_pk_mul_f32 v[22:23], v[78:79], v[84:85] op_sel_hi:[1,0]
	v_pk_mul_f32 v[26:27], v[74:75], v[26:27]
	v_add_f32_e32 v14, 1.0, v14
	v_add_f32_e32 v15, 1.0, v15
	v_rcp_f32_e32 v14, v14
	v_rcp_f32_e32 v15, v15
	v_pk_fma_f32 v[12:13], v[198:199], v[22:23], v[214:215] op_sel:[0,1,0] op_sel_hi:[1,0,1]
	v_pk_mul_f32 v[16:17], v[88:89], v[84:85] op_sel_hi:[1,0]
	v_pk_fma_f32 v[12:13], v[70:71], v[66:67], v[12:13] op_sel_hi:[0,1,1]
	v_pk_mul_f32 v[14:15], v[14:15], v[64:65]
	v_pk_fma_f32 v[2:3], v[200:201], v[16:17], v[216:217] op_sel:[0,1,0] op_sel_hi:[1,0,1]
	v_pk_mul_f32 v[12:13], v[14:15], v[12:13]
	v_mul_f32_e32 v14, 0xbfb8aa3b, v58
	v_mul_f32_e32 v6, 0xbfb8aa3b, v59
	v_exp_f32_e32 v14, v14
	v_exp_f32_e32 v6, v6
	v_pk_fma_f32 v[2:3], v[70:71], v[62:63], v[2:3] op_sel_hi:[0,1,1]
	v_pk_mul_f32 v[28:29], v[86:87], v[28:29]
	v_add_f32_e32 v14, 1.0, v14
	v_add_f32_e32 v6, 1.0, v6
	v_rcp_f32_e32 v14, v14
	v_rcp_f32_e32 v15, v6
	v_pk_mul_f32 v[18:19], v[98:99], v[18:19]
	v_pk_mul_f32 v[20:21], v[80:81], v[20:21]
	v_pk_fma_f32 v[10:11], v[70:71], v[68:69], v[10:11] op_sel_hi:[0,1,1]
	v_pk_mul_f32 v[6:7], v[14:15], v[58:59]
	v_pk_mul_f32 v[14:15], v[72:73], v[84:85] op_sel_hi:[1,0]
	v_pk_mul_f32 v[6:7], v[6:7], v[2:3]
	v_mul_f32_e32 v2, 0xbfb8aa3b, v48
	v_mul_f32_e32 v3, 0xbfb8aa3b, v49
	v_exp_f32_e32 v2, v2
	v_exp_f32_e32 v3, v3
	v_pk_fma_f32 v[4:5], v[14:15], v[202:203], v[218:219] op_sel:[1,0,0] op_sel_hi:[0,1,1]
	v_pk_fma_f32 v[4:5], v[70:71], v[50:51], v[4:5] op_sel_hi:[0,1,1]
	v_add_f32_e32 v2, 1.0, v2
	v_add_f32_e32 v3, 1.0, v3
	v_rcp_f32_e32 v2, v2
	v_rcp_f32_e32 v3, v3
	v_pk_mul_f32 v[10:11], v[82:83], v[10:11]
	v_pk_mul_f32 v[2:3], v[2:3], v[48:49]
	s_nop 0
	v_pk_mul_f32 v[8:9], v[2:3], v[4:5]
	v_cvt_pk_bf16_f32 v2, v26, v27
	v_cvt_pk_bf16_f32 v3, v28, v29
	v_cvt_pk_bf16_f32 v4, v18, v19
	v_cvt_pk_bf16_f32 v5, v20, v21
	global_store_dwordx4 v[46:47], v[2:5], off
	s_nop 1
	v_cvt_pk_bf16_f32 v2, v10, v11
	v_cvt_pk_bf16_f32 v3, v12, v13
	v_cvt_pk_bf16_f32 v4, v6, v7
	v_cvt_pk_bf16_f32 v5, v8, v9
	global_store_dwordx4 v[46:47], v[2:5], off offset:16
	s_cbranch_scc0 .LBB0_135
